# w2 + relaxed counted vmcnt waits in attention unit prologue (first S tile needs only Q and K0) + permlane-swap row-stat shuffles in SwiGLU epilogues
# baseline (speedup 1.0000x reference)
; __device__ __forceinline__ void attn_unit(LAS unsigned char* lds, int seq, int h, int qb, bf16_t* UQ, const bf16_t* KB, const bf16_t* VB, const float* rel_bias, const float* subln, float lam, float bmax) {
;     const int tid = threadIdx.x, lane = tid & 63, w = __builtin_amdgcn_readfirstlane(tid >> 6), r16 = lane & 15, fq = lane >> 4;
;     int row0, S; if (seq < NSEQ_P) { row0 = seq * SEQ_P; S = SEQ_P; } else { row0 = MP + (seq - NSEQ_P) * SEQ_S; S = SEQ_S; }
;     const int q0 = qb * 128, NT = S / 64, tmask = NT - 1, tstart = 2 * qb;
;     const LAS unsigned char* tab = lds + AT_TAB;
;     const unsigned lds0 = (unsigned)(size_t)lds;
;     if (tid < 257) ((LAS float*)(lds + AT_TAB))[tid] = LOG2E * (rel_bias[t5_bucket(tid - 128) * 4 + h] - bmax);
;     bf16x8 qf[2][2];
;     { const bf16_t* qp = UQ + (size_t)(row0 + q0 + 16 * w + r16) * DM + 512 + 128 * h + 8 * fq;
; #pragma unroll
;       for (int c = 0; c < 2; ++c)
; #pragma unroll
;           for (int kk = 0; kk < 2; ++kk) qf[c][kk] = *(const bf16x8*)(qp + 64 * c + 32 * kk); }
;     f32x4 o[2][8];
; #pragma unroll
;     for (int c = 0; c < 2; ++c)
; #pragma unroll
;         for (int d = 0; d < 8; ++d) o[c][d] = (f32x4){0.f, 0.f, 0.f, 0.f};
;     f32x4 ol[2] = {(f32x4){0.f, 0.f, 0.f, 0.f}, (f32x4){0.f, 0.f, 0.f, 0.f}};
;     unsigned kso[2], vso[2];
; #pragma unroll
;     for (int i = 0; i < 2; ++i) { const int row = 4 * (2 * w + i) + (lane >> 4), pos = lane & 15;
;         kso[i] = (unsigned)(row * 512 + 8 * (pos ^ (row & 15))) * 2u; vso[i] = (unsigned)(row * 512 + 8 * (pos ^ (2 * (row & 7)))) * 2u; }
;     const char* kg = (const char*)(KB + (size_t)row0 * 512 + 128 * h);
;     const char* vg = (const char*)(VB + (size_t)row0 * 512 + 128 * h);
;     ...
;     AT_STAGE(kg, kso, 0, AT_K0); AT_STAGE(vg, vso, 0, AT_V0); AT_STAGE(kg, kso, 1, AT_K0 + AT_TILE); AT_STAGE(vg, vso, 1, AT_V0 + AT_TILE); AT_STAGE(kg, kso, 2, AT_K0 + 2 * AT_TILE);
;     int kfo[2][2], vo[8];
; #pragma unroll
;     for (int c = 0; c < 2; ++c)
; #pragma unroll
;         for (int kk = 0; kk < 2; ++kk) kfo[c][kk] = r16 * 256 + (((8 * c + 4 * kk + fq) ^ r16) * 16);
;     { const int rk = 4 * (fq & 1) + (r16 >> 2);
; #pragma unroll
;       for (int dt = 0; dt < 8; ++dt) vo[dt] = (4 * fq + (r16 >> 2)) * 256 + ((dt ^ rk) * 32) + (r16 & 3) * 8; }
;     const int qrow = q0 + 16 * w;
;     const int tixb = (4 * fq - (qrow + r16) + 128) * 4;
.LBB0_505:
	s_or_b64 exec, exec, s[2:3]
	s_ashr_i32 s2, s44, 7
	s_add_i32 s23, s2, 16
	s_lshl_b32 s46, s23, 11
	s_lshl_b32 s23, s23, 12
	s_and_b32 s3, s44, 31
	s_lshr_b32 s22, s22, 6
	s_addk_i32 s23, 0x8000
	s_cmp_lt_i32 s2, 0
	s_cselect_b32 s45, 31, 63
	s_cselect_b32 s2, s46, s23
	s_lshl_b32 s23, s3, 7
	s_lshl_b32 s53, s22, 4
	s_lshl_b32 s46, s3, 1
	v_or_b32_e32 v2, s23, v177
	s_add_i32 s3, s53, s2
	v_add_u32_e32 v2, s3, v2
	s_lshl_b32 s3, s22, 3
	v_or_b32_e32 v18, s3, v178
	v_bitop3_b32 v20, s3, v171, v178 bitop3:0x36
	s_ashr_i32 s3, s2, 31
	s_lshl_b32 s20, s20, 8
	s_lshl_b64 s[2:3], s[2:3], 10
	s_add_u32 s47, s11, s2
	s_addc_u32 s48, s24, s3
	s_add_u32 s47, s47, s20
	s_addc_u32 s48, s48, 0
	s_add_u32 s50, s25, s2
	s_addc_u32 s51, s26, s3
	s_and_b32 s58, s45, s46
	s_lshl_b32 s52, s58, 16
	v_ashrrev_i32_e32 v3, 31, v2
	v_lshlrev_b32_e32 v19, 9, v18
	v_lshlrev_b32_e32 v20, 3, v20
	s_add_u32 s2, s47, s52
	v_lshlrev_b64 v[2:3], 11, v[2:3]
	v_and_or_b32 v20, v20, s33, v19
	v_or_b32_e32 v19, v19, v180
	s_addc_u32 s3, s48, 0
	s_lshl_b32 s22, s22, 11
	v_lshl_add_u64 v[2:3], s[36:37], 0, v[2:3]
	v_lshlrev_b32_e32 v164, 1, v19
	v_or_b32_e32 v19, 4, v18
	v_bitop3_b32 v18, v18, v171, 4 bitop3:0x36
	s_add_i32 s49, s22, 0
	v_lshl_add_u64 v[162:163], v[2:3], 0, s[20:21]
	v_mov_b32_e32 v161, v155
	v_lshlrev_b32_e32 v19, 9, v19
	v_lshlrev_b32_e32 v18, 3, v18
	s_add_i32 s54, s49, 0x400
	v_lshl_add_u64 v[14:15], v[162:163], 0, v[160:161]
	v_lshlrev_b32_e32 v154, 1, v20
	v_and_or_b32 v18, v18, s33, v19
	s_mov_b32 m0, s49
	s_add_u32 s20, s50, s20
	global_load_dwordx4 v[2:5], v[14:15], off offset:1024
	global_load_dwordx4 v[6:9], v[14:15], off offset:1088
	global_load_dwordx4 v[10:13], v[14:15], off offset:1152
	s_nop 0
	global_load_dwordx4 v[14:17], v[14:15], off offset:1216
	v_lshlrev_b32_e32 v166, 1, v18
	global_load_lds_dwordx4 v154, s[2:3]
	s_mov_b32 m0, s54
	s_addc_u32 s50, s51, 0
	global_load_lds_dwordx4 v166, s[2:3]
	s_add_u32 s2, s20, s52
	v_or_b32_e32 v18, v19, v181
	s_addc_u32 s3, s50, 0
	s_add_i32 m0, s49, 0xc000
	v_lshlrev_b32_e32 v168, 1, v18
	global_load_lds_dwordx4 v164, s[2:3]
	s_add_i32 m0, s49, 0xc400
	v_mov_b32_e32 v19, s42
	global_load_lds_dwordx4 v168, s[2:3]
	s_or_b32 s2, s46, 1
	s_and_b32 s52, s2, s45
	s_lshl_b32 s22, s52, 16
	s_add_u32 s2, s47, s22
	s_addc_u32 s3, s48, 0
	s_add_i32 m0, s49, 0x4000
	s_nop 0
	global_load_lds_dwordx4 v154, s[2:3]
	s_add_i32 m0, s49, 0x4400
	s_nop 0
	global_load_lds_dwordx4 v166, s[2:3]
	s_add_u32 s2, s20, s22
	s_addc_u32 s3, s50, 0
	s_add_i32 m0, s49, 0x10000
	s_nop 0
	global_load_lds_dwordx4 v164, s[2:3]
	s_add_i32 m0, s49, 0x10400
	s_nop 0
	global_load_lds_dwordx4 v168, s[2:3]
	s_add_i32 s2, s46, 2
	s_and_b32 s2, s2, s45
	s_lshl_b32 s55, s2, 16
	s_add_u32 s2, s47, s55
	s_addc_u32 s3, s48, 0
	s_add_i32 m0, s49, 0x8000
	s_add_i32 s53, s53, s23
	global_load_lds_dwordx4 v154, s[2:3]
	s_add_i32 m0, s49, 0x8400
	v_or_b32_e32 v18, s53, v177
	global_load_lds_dwordx4 v166, s[2:3]
	s_lshl_b32 s2, s58, 6
	v_sub_u32_e32 v18, v156, v18
	s_or_b32 s3, s2, 63
	s_or_b32 s51, s53, 15
	v_lshl_add_u32 v161, v18, 2, v212
	s_waitcnt vmcnt(8) lgkmcnt(0)
	s_barrier
	v_mov_b32_e32 v18, s27
	s_sub_i32 s3, s3, s53
	s_sub_i32 s2, s2, s51
	ds_read_b32 v214, v18
	ds_read_b32 v215, v19
	s_cmpk_lt_i32 s3, 0xff81
	s_cselect_b64 s[22:23], -1, 0
	s_cmpk_gt_i32 s2, 0x7f
	s_cselect_b64 s[2:3], -1, 0
	s_or_b64 s[60:61], s[22:23], s[2:3]
	s_mov_b64 s[22:23], -1
	s_and_b64 vcc, exec, s[60:61]
	s_cbranch_vccnz .LBB0_507
	v_lshl_add_u32 v26, s58, 8, v161
	v_add_u32_e32 v30, 0x8c, v26
	v_med3_i32 v30, v30, 0, v213
	v_add_u32_e32 v33, s27, v30
	v_add_u32_e32 v30, 0xc0, v26
	v_med3_i32 v30, v30, 0, v213
	v_add_u32_e32 v34, s27, v30
	v_add_u32_e32 v30, 0xc4, v26
	v_med3_i32 v30, v30, 0, v213
	v_add_u32_e32 v19, 4, v26
	v_add_u32_e32 v20, 8, v26
	v_add_u32_e32 v21, 12, v26
	v_add_u32_e32 v22, 64, v26
	v_add_u32_e32 v23, 0x44, v26
	v_add_u32_e32 v24, 0x48, v26
	v_add_u32_e32 v25, 0x4c, v26
	v_add_u32_e32 v27, 0x80, v26
	v_add_u32_e32 v35, s27, v30
	v_add_u32_e32 v30, 0xc8, v26
	v_med3_i32 v18, v26, 0, v213
	v_med3_i32 v19, v19, 0, v213
	v_med3_i32 v20, v20, 0, v213
	v_med3_i32 v21, v21, 0, v213
	v_med3_i32 v22, v22, 0, v213
	v_med3_i32 v23, v23, 0, v213
	v_med3_i32 v24, v24, 0, v213
	v_med3_i32 v25, v25, 0, v213
	v_med3_i32 v27, v27, 0, v213
	v_add_u32_e32 v28, 0x84, v26
	v_add_u32_e32 v29, 0x88, v26
	v_med3_i32 v30, v30, 0, v213
	v_add_u32_e32 v26, 0xcc, v26
	v_add_u32_e32 v18, s27, v18
	v_add_u32_e32 v19, s27, v19
	v_add_u32_e32 v20, s27, v20
	v_add_u32_e32 v21, s27, v21
	v_add_u32_e32 v22, s27, v22
	v_add_u32_e32 v23, s27, v23
	v_add_u32_e32 v24, s27, v24
	v_add_u32_e32 v25, s27, v25
	v_add_u32_e32 v27, s27, v27
	v_med3_i32 v28, v28, 0, v213
	v_med3_i32 v29, v29, 0, v213
	v_add_u32_e32 v36, s27, v30
	v_med3_i32 v26, v26, 0, v213
	ds_read_b32 v18, v18
	ds_read_b32 v19, v19
	ds_read_b32 v20, v20
	ds_read_b32 v21, v21
	ds_read_b32 v22, v22
	ds_read_b32 v23, v23
	ds_read_b32 v24, v24
	ds_read_b32 v25, v25
	v_add_u32_e32 v28, s27, v28
	v_add_u32_e32 v29, s27, v29
	v_add_u32_e32 v26, s27, v26
	ds_read_b32 v30, v27
	ds_read_b32 v31, v28
	ds_read_b32 v32, v29
	ds_read_b32 v33, v33
	ds_read_b32 v34, v34
	ds_read_b32 v35, v35
	ds_read_b32 v36, v36
	ds_read_b32 v37, v26
	s_mov_b64 s[22:23], 0

; #define LAS __attribute__((address_space(3)))
; #define AT_STAGE(gbase, so, i, ldsoff) do { const int _ii = (i) < NT ? (i) : NT - 1; const size_t _go = (size_t)((tstart + _ii) & tmask) * (64 * 1024); _Pragma("unroll") for (int _i = 0; _i < 2; ++_i) \
;         __builtin_amdgcn_global_load_lds((const unsigned*)((gbase) + _go + (so)[_i]), (LAS unsigned*)(lds + (ldsoff) + (2 * w + _i) * 1024), 16, 0, 0); } while (0)
; #define AT_BAR(N) asm volatile("s_waitcnt vmcnt(" #N ") lgkmcnt(0)\n\ts_barrier" ::: "memory")
; __device__ __forceinline__ void attn_unit(LAS unsigned char* lds, int seq, int h, int qb, bf16_t* UQ, const bf16_t* KB, const bf16_t* VB, const float* rel_bias, const float* subln, float lam, float bmax) {
;     ...
; #pragma unroll
;     for (int kt = 0; kt < 4; ++kt) {
; #pragma unroll
;         for (int c = 0; c < 2; ++c) {
;             f32x4 a = tbv[kt];
; #pragma unroll
;             for (int kk = 0; kk < 2; ++kk) { const bf16x8 kf = *(const LAS bf16x8*)(lds + AT_K0 + kfo[c][kk] + kt * 4096); a = __builtin_amdgcn_mfma_f32_16x16x32_bf16(kf, qf[c][kk], a, 0, 0, 0); }
;             s[c][kt] = a;
;         }
;     }
;     AT_BAR(0);
;     AT_STAGE(kg, kso, 3, AT_K0); AT_STAGE(vg, vso, 2, AT_V0 + 2 * AT_TILE);
;     AT_TB((tstart + 1) & tmask);
.LBB0_509:
	v_add_u32_e32 v67, 0, v182
	v_add_u32_e32 v66, 0, v184
	ds_read_b128 v[26:29], v67
	ds_read_b128 v[38:41], v67 offset:4096
	ds_read_b128 v[42:45], v66
	ds_read_b128 v[50:53], v66 offset:4096
	v_add_u32_e32 v69, 0, v183
	v_add_u32_e32 v68, 0, v185
	s_add_i32 s2, s46, 3
	s_and_b32 s2, s2, s45
	s_waitcnt vmcnt(8) lgkmcnt(0)
	v_mfma_f32_16x16x32_bf16 v[26:29], v[26:29], v[2:5], v[18:21]
	ds_read_b128 v[46:49], v69 offset:4096
	s_lshl_b32 s2, s2, 16
	s_add_u32 s2, s47, s2
	v_mfma_f32_16x16x32_bf16 v[18:21], v[42:45], v[10:13], v[18:21]
	ds_read_b128 v[42:45], v69
	s_addc_u32 s3, s48, 0
	s_mov_b32 m0, s49
	s_waitcnt lgkmcnt(0)
	v_mfma_f32_16x16x32_bf16 v[42:45], v[42:45], v[6:9], v[26:29]
	s_nop 2
	ds_read_b128 v[26:29], v68
	ds_read_b128 v[54:57], v68 offset:4096
	v_mov_b32_e32 v167, v155
	v_mov_b32_e32 v165, v155
	s_waitcnt lgkmcnt(1)
	v_mfma_f32_16x16x32_bf16 v[18:21], v[26:29], v[14:17], v[18:21]
	v_mov_b32_e32 v169, v155
	v_mfma_f32_16x16x32_bf16 v[26:29], v[38:41], v[2:5], v[22:25]
	ds_read_b128 v[38:41], v67 offset:8192
	ds_read_b128 v[58:61], v67 offset:12288
	v_mfma_f32_16x16x32_bf16 v[22:25], v[50:53], v[10:13], v[22:25]
	ds_read_b128 v[50:53], v69 offset:8192
	ds_read_b128 v[62:65], v69 offset:12288
	ds_read_b128 v[70:73], v66 offset:8192
	ds_read_b128 v[74:77], v66 offset:12288
	v_mfma_f32_16x16x32_bf16 v[46:49], v[46:49], v[6:9], v[26:29]
	s_waitcnt lgkmcnt(6)
	v_mfma_f32_16x16x32_bf16 v[26:29], v[54:57], v[14:17], v[22:25]
	ds_read_b128 v[54:57], v68 offset:8192
	ds_read_b128 v[78:81], v68 offset:12288
	s_waitcnt vmcnt(4) lgkmcnt(0)
	s_barrier
	s_waitcnt lgkmcnt(7)
	v_mfma_f32_16x16x32_bf16 v[22:25], v[38:41], v[2:5], v[30:33]
	v_lshl_add_u64 v[38:39], s[2:3], 0, v[154:155]
	global_load_lds_dwordx4 v[38:39], off
	v_lshl_add_u64 v[38:39], s[2:3], 0, v[166:167]
	s_add_u32 s2, s20, s55
	s_mov_b32 m0, s54
	s_addc_u32 s3, s50, 0
	s_waitcnt lgkmcnt(0)
	v_mfma_f32_16x16x32_bf16 v[22:25], v[50:53], v[6:9], v[22:25]
	global_load_lds_dwordx4 v[38:39], off
	s_add_i32 m0, s49, 0x14000
	v_lshl_add_u64 v[50:51], s[2:3], 0, v[164:165]
	global_load_lds_dwordx4 v[50:51], off
	v_lshl_add_u64 v[50:51], s[2:3], 0, v[168:169]
	s_add_i32 m0, s49, 0x14400
	v_mfma_f32_16x16x32_bf16 v[30:33], v[70:73], v[10:13], v[30:33]
	global_load_lds_dwordx4 v[50:51], off
	s_lshl_b32 s2, s52, 6
	v_mfma_f32_16x16x32_bf16 v[38:41], v[58:61], v[2:5], v[34:37]
	s_or_b32 s3, s2, 63
	s_sub_i32 s3, s3, s53
	s_sub_i32 s2, s2, s51
	v_mfma_f32_16x16x32_bf16 v[34:37], v[74:77], v[10:13], v[34:37]
	s_cmpk_lt_i32 s3, 0xff81
	s_cselect_b64 s[22:23], -1, 0
	s_cmpk_gt_i32 s2, 0x7f
	v_mfma_f32_16x16x32_bf16 v[30:33], v[54:57], v[14:17], v[30:33]
	s_cselect_b64 s[2:3], -1, 0
	s_or_b64 s[54:55], s[22:23], s[2:3]
	s_mov_b64 s[22:23], -1
	v_mfma_f32_16x16x32_bf16 v[38:41], v[62:65], v[6:9], v[38:41]
	s_and_b64 vcc, exec, s[54:55]
	v_mfma_f32_16x16x32_bf16 v[34:37], v[78:81], v[14:17], v[34:37]
	s_cbranch_vccnz .LBB0_511
	v_lshl_add_u32 v54, s52, 8, v161
	v_add_u32_e32 v51, 4, v54
	v_add_u32_e32 v52, 8, v54
	v_add_u32_e32 v53, 12, v54
	v_add_u32_e32 v58, 0x4c, v54
	v_med3_i32 v50, v54, 0, v213
	v_med3_i32 v51, v51, 0, v213
	v_med3_i32 v52, v52, 0, v213
	v_med3_i32 v53, v53, 0, v213
	v_add_u32_e32 v55, 64, v54
	v_add_u32_e32 v56, 0x44, v54
	v_add_u32_e32 v57, 0x48, v54
	v_med3_i32 v58, v58, 0, v213
	v_add_u32_e32 v50, s27, v50
	v_add_u32_e32 v51, s27, v51
	v_add_u32_e32 v52, s27, v52
	v_add_u32_e32 v53, s27, v53
	v_med3_i32 v55, v55, 0, v213
	v_med3_i32 v56, v56, 0, v213
	v_med3_i32 v57, v57, 0, v213
	v_add_u32_e32 v62, s27, v58
	v_add_u32_e32 v55, s27, v55
	v_add_u32_e32 v56, s27, v56
	v_add_u32_e32 v57, s27, v57
	ds_read_b32 v58, v50
	ds_read_b32 v59, v51
	ds_read_b32 v60, v52
	ds_read_b32 v61, v53
	ds_read_b32 v50, v55
	ds_read_b32 v51, v56
	ds_read_b32 v52, v57
	ds_read_b32 v53, v62
	v_add_u32_e32 v62, 0x8c, v54
	v_med3_i32 v62, v62, 0, v213
	v_add_u32_e32 v65, s27, v62
	v_add_u32_e32 v62, 0xc0, v54
	v_med3_i32 v62, v62, 0, v213
	v_add_u32_e32 v70, s27, v62
	v_add_u32_e32 v62, 0xc4, v54
	v_add_u32_e32 v55, 0x80, v54
	v_add_u32_e32 v56, 0x84, v54
	v_add_u32_e32 v57, 0x88, v54
	v_med3_i32 v62, v62, 0, v213
	v_med3_i32 v55, v55, 0, v213
	v_med3_i32 v56, v56, 0, v213
	v_med3_i32 v57, v57, 0, v213
	v_add_u32_e32 v71, s27, v62
	v_add_u32_e32 v62, 0xc8, v54
	v_add_u32_e32 v54, 0xcc, v54
	v_add_u32_e32 v55, s27, v55
	v_add_u32_e32 v56, s27, v56
	v_add_u32_e32 v57, s27, v57
	v_med3_i32 v62, v62, 0, v213
	v_med3_i32 v54, v54, 0, v213
	v_add_u32_e32 v72, s27, v62
	v_add_u32_e32 v73, s27, v54
	ds_read_b32 v62, v55
	ds_read_b32 v63, v56
	ds_read_b32 v64, v57
	ds_read_b32 v65, v65
	ds_read_b32 v54, v70
	ds_read_b32 v55, v71
	ds_read_b32 v56, v72
	ds_read_b32 v57, v73
	s_mov_b64 s[22:23], 0

; __device__ __forceinline__ void attn_unit(LAS unsigned char* lds, int seq, int h, int qb, bf16_t* UQ, const bf16_t* KB, const bf16_t* VB, const float* rel_bias, const float* subln, float lam, float bmax) {
;     const int tid = threadIdx.x, lane = tid & 63, w = __builtin_amdgcn_readfirstlane(tid >> 6), r16 = lane & 15, fq = lane >> 4;
;     int row0, S; if (seq < NSEQ_P) { row0 = seq * SEQ_P; S = SEQ_P; } else { row0 = MP + (seq - NSEQ_P) * SEQ_S; S = SEQ_S; }
;     const int q0 = qb * 128, NT = S / 64, tmask = NT - 1, tstart = 2 * qb;
;     const LAS unsigned char* tab = lds + AT_TAB;
;     const unsigned lds0 = (unsigned)(size_t)lds;
;     if (tid < 257) ((LAS float*)(lds + AT_TAB))[tid] = LOG2E * (rel_bias[t5_bucket(tid - 128) * 4 + h] - bmax);
;     bf16x8 qf[2][2];
;     { const bf16_t* qp = UQ + (size_t)(row0 + q0 + 16 * w + r16) * DM + 512 + 128 * h + 8 * fq;
; #pragma unroll
;       for (int c = 0; c < 2; ++c)
; #pragma unroll
;           for (int kk = 0; kk < 2; ++kk) qf[c][kk] = *(const bf16x8*)(qp + 64 * c + 32 * kk); }
;     f32x4 o[2][8];
; #pragma unroll
;     for (int c = 0; c < 2; ++c)
; #pragma unroll
;         for (int d = 0; d < 8; ++d) o[c][d] = (f32x4){0.f, 0.f, 0.f, 0.f};
;     f32x4 ol[2] = {(f32x4){0.f, 0.f, 0.f, 0.f}, (f32x4){0.f, 0.f, 0.f, 0.f}};
;     unsigned kso[2], vso[2];
; #pragma unroll
;     for (int i = 0; i < 2; ++i) { const int row = 4 * (2 * w + i) + (lane >> 4), pos = lane & 15;
;         kso[i] = (unsigned)(row * 512 + 8 * (pos ^ (row & 15))) * 2u; vso[i] = (unsigned)(row * 512 + 8 * (pos ^ (2 * (row & 7)))) * 2u; }
;     const char* kg = (const char*)(KB + (size_t)row0 * 512 + 128 * h);
;     const char* vg = (const char*)(VB + (size_t)row0 * 512 + 128 * h);
;     ...
;     AT_STAGE(kg, kso, 0, AT_K0); AT_STAGE(vg, vso, 0, AT_V0); AT_STAGE(kg, kso, 1, AT_K0 + AT_TILE); AT_STAGE(vg, vso, 1, AT_V0 + AT_TILE); AT_STAGE(kg, kso, 2, AT_K0 + 2 * AT_TILE);
;     int kfo[2][2], vo[8];
; #pragma unroll
;     for (int c = 0; c < 2; ++c)
; #pragma unroll
;         for (int kk = 0; kk < 2; ++kk) kfo[c][kk] = r16 * 256 + (((8 * c + 4 * kk + fq) ^ r16) * 16);
;     { const int rk = 4 * (fq & 1) + (r16 >> 2);
; #pragma unroll
;       for (int dt = 0; dt < 8; ++dt) vo[dt] = (4 * fq + (r16 >> 2)) * 256 + ((dt ^ rk) * 32) + (r16 & 3) * 8; }
;     const int qrow = q0 + 16 * w;
;     const int tixb = (4 * fq - (qrow + r16) + 128) * 4;
.LBB0_525:
	s_or_b64 exec, exec, s[2:3]
	s_and_b32 s55, s43, 15
	s_lshr_b32 s23, s22, 6
	s_lshl_b32 s2, s43, 5
	s_and_b32 s2, s2, 0xfffff800
	s_lshl_b32 s56, s55, 7
	s_lshl_b32 s3, s23, 3
	v_or_b32_e32 v2, s56, v177
	v_or_b32_e32 v18, s3, v178
	v_bitop3_b32 v20, s3, v171, v178 bitop3:0x36
	s_ashr_i32 s3, s2, 31
	s_lshl_b32 s44, s55, 1
	s_lshl_b32 s51, s23, 4
	v_or_b32_e32 v2, s2, v2
	s_lshl_b32 s20, s20, 8
	s_lshl_b64 s[2:3], s[2:3], 10
	s_add_u32 s45, s11, s2
	s_addc_u32 s46, s24, s3
	s_add_u32 s45, s45, s20
	s_addc_u32 s46, s46, 0
	s_add_u32 s48, s25, s2
	v_add_u32_e32 v2, s51, v2
	s_addc_u32 s49, s26, s3
	s_lshl_b32 s53, s55, 17
	v_ashrrev_i32_e32 v3, 31, v2
	v_lshlrev_b32_e32 v19, 9, v18
	v_lshlrev_b32_e32 v20, 3, v20
	s_add_u32 s2, s45, s53
	v_lshlrev_b64 v[2:3], 11, v[2:3]
	v_and_or_b32 v20, v20, s33, v19
	v_or_b32_e32 v19, v19, v180
	s_addc_u32 s3, s46, 0
	s_lshl_b32 s23, s23, 11
	v_lshl_add_u64 v[2:3], s[36:37], 0, v[2:3]
	v_lshlrev_b32_e32 v164, 1, v19
	v_or_b32_e32 v19, 4, v18
	v_bitop3_b32 v18, v18, v171, 4 bitop3:0x36
	s_add_i32 s47, s23, 0
	v_lshl_add_u64 v[162:163], v[2:3], 0, s[20:21]
	v_lshlrev_b32_e32 v19, 9, v19
	v_lshlrev_b32_e32 v18, 3, v18
	s_add_i32 s52, s47, 0x400
	v_lshl_add_u64 v[14:15], v[162:163], 0, v[160:161]
	v_lshlrev_b32_e32 v154, 1, v20
	v_and_or_b32 v18, v18, s33, v19
	s_mov_b32 m0, s47
	s_add_u32 s20, s48, s20
	global_load_dwordx4 v[2:5], v[14:15], off offset:1024
	global_load_dwordx4 v[6:9], v[14:15], off offset:1088
	global_load_dwordx4 v[10:13], v[14:15], off offset:1152
	s_nop 0
	global_load_dwordx4 v[14:17], v[14:15], off offset:1216
	v_lshlrev_b32_e32 v166, 1, v18
	global_load_lds_dwordx4 v154, s[2:3]
	s_mov_b32 m0, s52
	s_addc_u32 s48, s49, 0
	global_load_lds_dwordx4 v166, s[2:3]
	s_add_u32 s2, s20, s53
	v_or_b32_e32 v18, v19, v181
	s_addc_u32 s3, s48, 0
	s_add_i32 m0, s47, 0xc000
	s_or_b32 s50, s44, 1
	v_lshlrev_b32_e32 v168, 1, v18
	global_load_lds_dwordx4 v164, s[2:3]
	s_add_i32 m0, s47, 0xc400
	s_lshl_b32 s23, s50, 16
	global_load_lds_dwordx4 v168, s[2:3]
	s_add_u32 s2, s45, s23
	s_addc_u32 s3, s46, 0
	s_add_i32 m0, s47, 0x4000
	s_nop 0
	global_load_lds_dwordx4 v154, s[2:3]
	s_add_i32 m0, s47, 0x4400
	s_nop 0
	global_load_lds_dwordx4 v166, s[2:3]
	s_add_u32 s2, s20, s23
	s_addc_u32 s3, s48, 0
	s_add_i32 m0, s47, 0x10000
	s_nop 0
	global_load_lds_dwordx4 v164, s[2:3]
	s_add_i32 m0, s47, 0x10400
	s_nop 0
	global_load_lds_dwordx4 v168, s[2:3]
	s_add_i32 s2, s53, 0x20000
	s_and_b32 s54, s2, 0x1e0000
	s_add_u32 s2, s45, s54
	s_addc_u32 s3, s46, 0
	s_add_i32 m0, s47, 0x8000
	s_add_i32 s51, s51, s56
	global_load_lds_dwordx4 v154, s[2:3]
	s_add_i32 m0, s47, 0x8400
	s_or_b32 s49, s51, 15
	global_load_lds_dwordx4 v166, s[2:3]
	s_waitcnt vmcnt(8) lgkmcnt(0)
	s_barrier
	s_sub_i32 s2, s56, s49
	ds_read_b32 v215, v211
	ds_read_b32 v216, v212
	s_cmpk_gt_u32 s22, 0x2ff
	s_cselect_b64 s[22:23], -1, 0
	s_cmpk_gt_i32 s2, 0x7f
	v_or_b32_e32 v18, s51, v177
	s_cselect_b64 s[2:3], -1, 0
	v_sub_u32_e32 v18, v156, v18
	s_or_b64 s[56:57], s[22:23], s[2:3]
	v_lshl_add_u32 v214, v18, 2, v210
	s_mov_b64 s[22:23], -1
	s_and_b64 vcc, exec, s[56:57]
	s_cbranch_vccnz .LBB0_527
	v_lshl_add_u32 v26, s55, 9, v214
	v_add_u32_e32 v30, 0x8c, v26
	v_med3_i32 v30, v30, 0, v213
	v_add_u32_e32 v33, s27, v30
	v_add_u32_e32 v30, 0xc0, v26
	v_med3_i32 v30, v30, 0, v213
	v_add_u32_e32 v34, s27, v30
	v_add_u32_e32 v30, 0xc4, v26
	v_med3_i32 v30, v30, 0, v213
	v_add_u32_e32 v19, 4, v26
	v_add_u32_e32 v20, 8, v26
	v_add_u32_e32 v21, 12, v26
	v_add_u32_e32 v22, 64, v26
	v_add_u32_e32 v23, 0x44, v26
	v_add_u32_e32 v24, 0x48, v26
	v_add_u32_e32 v25, 0x4c, v26
	v_add_u32_e32 v27, 0x80, v26
	v_add_u32_e32 v35, s27, v30
	v_add_u32_e32 v30, 0xc8, v26
	v_med3_i32 v18, v26, 0, v213
	v_med3_i32 v19, v19, 0, v213
	v_med3_i32 v20, v20, 0, v213
	v_med3_i32 v21, v21, 0, v213
	v_med3_i32 v22, v22, 0, v213
	v_med3_i32 v23, v23, 0, v213
	v_med3_i32 v24, v24, 0, v213
	v_med3_i32 v25, v25, 0, v213
	v_med3_i32 v27, v27, 0, v213
	v_add_u32_e32 v28, 0x84, v26
	v_add_u32_e32 v29, 0x88, v26
	v_med3_i32 v30, v30, 0, v213
	v_add_u32_e32 v26, 0xcc, v26
	v_add_u32_e32 v18, s27, v18
	v_add_u32_e32 v19, s27, v19
	v_add_u32_e32 v20, s27, v20
	v_add_u32_e32 v21, s27, v21
	v_add_u32_e32 v22, s27, v22
	v_add_u32_e32 v23, s27, v23
	v_add_u32_e32 v24, s27, v24
	v_add_u32_e32 v25, s27, v25
	v_add_u32_e32 v27, s27, v27
	v_med3_i32 v28, v28, 0, v213
	v_med3_i32 v29, v29, 0, v213
	v_add_u32_e32 v36, s27, v30
	v_med3_i32 v26, v26, 0, v213
	ds_read_b32 v18, v18
	ds_read_b32 v19, v19
	ds_read_b32 v20, v20
	ds_read_b32 v21, v21
	ds_read_b32 v22, v22
	ds_read_b32 v23, v23
	ds_read_b32 v24, v24
	ds_read_b32 v25, v25
	v_add_u32_e32 v28, s27, v28
	v_add_u32_e32 v29, s27, v29
	v_add_u32_e32 v26, s27, v26
	ds_read_b32 v30, v27
	ds_read_b32 v31, v28
	ds_read_b32 v32, v29
	ds_read_b32 v33, v33
	ds_read_b32 v34, v34
	ds_read_b32 v35, v35
	ds_read_b32 v36, v36
	ds_read_b32 v37, v26
	s_mov_b64 s[22:23], 0

; #define LAS __attribute__((address_space(3)))
; #define AT_STAGE(gbase, so, i, ldsoff) do { const int _ii = (i) < NT ? (i) : NT - 1; const size_t _go = (size_t)((tstart + _ii) & tmask) * (64 * 1024); _Pragma("unroll") for (int _i = 0; _i < 2; ++_i) \
;         __builtin_amdgcn_global_load_lds((const unsigned*)((gbase) + _go + (so)[_i]), (LAS unsigned*)(lds + (ldsoff) + (2 * w + _i) * 1024), 16, 0, 0); } while (0)
; #define AT_BAR(N) asm volatile("s_waitcnt vmcnt(" #N ") lgkmcnt(0)\n\ts_barrier" ::: "memory")
; __device__ __forceinline__ void attn_unit(LAS unsigned char* lds, int seq, int h, int qb, bf16_t* UQ, const bf16_t* KB, const bf16_t* VB, const float* rel_bias, const float* subln, float lam, float bmax) {
;     ...
; #pragma unroll
;     for (int kt = 0; kt < 4; ++kt) {
; #pragma unroll
;         for (int c = 0; c < 2; ++c) {
;             f32x4 a = tbv[kt];
; #pragma unroll
;             for (int kk = 0; kk < 2; ++kk) { const bf16x8 kf = *(const LAS bf16x8*)(lds + AT_K0 + kfo[c][kk] + kt * 4096); a = __builtin_amdgcn_mfma_f32_16x16x32_bf16(kf, qf[c][kk], a, 0, 0, 0); }
;             s[c][kt] = a;
;         }
;     }
;     AT_BAR(0);
;     AT_STAGE(kg, kso, 3, AT_K0); AT_STAGE(vg, vso, 2, AT_V0 + 2 * AT_TILE);
;     AT_TB((tstart + 1) & tmask);
.LBB0_529:
	v_add_u32_e32 v67, 0, v176
	v_add_u32_e32 v66, 0, v183
	ds_read_b128 v[26:29], v67
	ds_read_b128 v[38:41], v67 offset:4096
	ds_read_b128 v[42:45], v66
	ds_read_b128 v[50:53], v66 offset:4096
	v_add_u32_e32 v69, 0, v182
	v_add_u32_e32 v68, 0, v184
	s_add_i32 s53, s53, 0x30000
	s_and_b32 s2, s53, 0x1f0000
	s_waitcnt vmcnt(8) lgkmcnt(0)
	v_mfma_f32_16x16x32_bf16 v[26:29], v[26:29], v[2:5], v[18:21]
	ds_read_b128 v[46:49], v69 offset:4096
	s_add_u32 s2, s45, s2
	s_addc_u32 s3, s46, 0
	v_mfma_f32_16x16x32_bf16 v[18:21], v[42:45], v[10:13], v[18:21]
	ds_read_b128 v[42:45], v69
	s_mov_b32 m0, s47
	v_mov_b32_e32 v167, v155
	s_waitcnt lgkmcnt(0)
	v_mfma_f32_16x16x32_bf16 v[42:45], v[42:45], v[6:9], v[26:29]
	s_nop 2
	ds_read_b128 v[26:29], v68
	ds_read_b128 v[54:57], v68 offset:4096
	v_mov_b32_e32 v165, v155
	v_mov_b32_e32 v169, v155
	s_waitcnt lgkmcnt(1)
	v_mfma_f32_16x16x32_bf16 v[18:21], v[26:29], v[14:17], v[18:21]
	v_mfma_f32_16x16x32_bf16 v[26:29], v[38:41], v[2:5], v[22:25]
	v_mfma_f32_16x16x32_bf16 v[22:25], v[50:53], v[10:13], v[22:25]
	ds_read_b128 v[38:41], v67 offset:8192
	ds_read_b128 v[50:53], v67 offset:12288
	ds_read_b128 v[58:61], v69 offset:8192
	ds_read_b128 v[62:65], v69 offset:12288
	v_mfma_f32_16x16x32_bf16 v[46:49], v[46:49], v[6:9], v[26:29]
	s_waitcnt lgkmcnt(4)
	v_mfma_f32_16x16x32_bf16 v[26:29], v[54:57], v[14:17], v[22:25]
	ds_read_b128 v[54:57], v66 offset:8192
	ds_read_b128 v[70:73], v66 offset:12288
	ds_read_b128 v[74:77], v68 offset:8192
	ds_read_b128 v[78:81], v68 offset:12288
	s_waitcnt vmcnt(4) lgkmcnt(0)
	s_barrier
	s_waitcnt lgkmcnt(7)
	v_mfma_f32_16x16x32_bf16 v[22:25], v[38:41], v[2:5], v[30:33]
	v_lshl_add_u64 v[38:39], s[2:3], 0, v[154:155]
	global_load_lds_dwordx4 v[38:39], off
	v_lshl_add_u64 v[38:39], s[2:3], 0, v[166:167]
	s_add_u32 s2, s20, s54
	s_mov_b32 m0, s52
	s_addc_u32 s3, s48, 0
	global_load_lds_dwordx4 v[38:39], off
	s_waitcnt lgkmcnt(0)
	v_mfma_f32_16x16x32_bf16 v[38:41], v[50:53], v[2:5], v[34:37]
	s_add_i32 m0, s47, 0x14000
	v_lshl_add_u64 v[50:51], s[2:3], 0, v[164:165]
	global_load_lds_dwordx4 v[50:51], off
	v_lshl_add_u64 v[50:51], s[2:3], 0, v[168:169]
	s_add_i32 m0, s47, 0x14400
	v_mfma_f32_16x16x32_bf16 v[30:33], v[54:57], v[10:13], v[30:33]
	global_load_lds_dwordx4 v[50:51], off
	s_lshl_b32 s2, s50, 6
	v_mfma_f32_16x16x32_bf16 v[34:37], v[70:73], v[10:13], v[34:37]
	s_or_b32 s3, s2, 63
	s_sub_i32 s3, s3, s51
	s_sub_i32 s2, s2, s49
	s_cmpk_lt_i32 s3, 0xff81
	v_mfma_f32_16x16x32_bf16 v[22:25], v[58:61], v[6:9], v[22:25]
	s_cselect_b64 s[22:23], -1, 0
	s_cmpk_gt_i32 s2, 0x7f
	s_cselect_b64 s[2:3], -1, 0
	v_mfma_f32_16x16x32_bf16 v[30:33], v[74:77], v[14:17], v[30:33]
	s_or_b64 s[52:53], s[22:23], s[2:3]
	s_mov_b64 s[22:23], -1
	s_and_b64 vcc, exec, s[52:53]
	v_mfma_f32_16x16x32_bf16 v[38:41], v[62:65], v[6:9], v[38:41]
	v_mfma_f32_16x16x32_bf16 v[34:37], v[78:81], v[14:17], v[34:37]
	s_cbranch_vccnz .LBB0_531
	v_lshl_add_u32 v54, s50, 8, v214
	v_add_u32_e32 v51, 4, v54
	v_add_u32_e32 v52, 8, v54
	v_add_u32_e32 v53, 12, v54
	v_add_u32_e32 v58, 0x4c, v54
	v_med3_i32 v50, v54, 0, v213
	v_med3_i32 v51, v51, 0, v213
	v_med3_i32 v52, v52, 0, v213
	v_med3_i32 v53, v53, 0, v213
	v_add_u32_e32 v55, 64, v54
	v_add_u32_e32 v56, 0x44, v54
	v_add_u32_e32 v57, 0x48, v54
	v_med3_i32 v58, v58, 0, v213
	v_add_u32_e32 v50, s27, v50
	v_add_u32_e32 v51, s27, v51
	v_add_u32_e32 v52, s27, v52
	v_add_u32_e32 v53, s27, v53
	v_med3_i32 v55, v55, 0, v213
	v_med3_i32 v56, v56, 0, v213
	v_med3_i32 v57, v57, 0, v213
	v_add_u32_e32 v62, s27, v58
	v_add_u32_e32 v55, s27, v55
	v_add_u32_e32 v56, s27, v56
	v_add_u32_e32 v57, s27, v57
	ds_read_b32 v58, v50
	ds_read_b32 v59, v51
	ds_read_b32 v60, v52
	ds_read_b32 v61, v53
	ds_read_b32 v50, v55
	ds_read_b32 v51, v56
	ds_read_b32 v52, v57
	ds_read_b32 v53, v62
	v_add_u32_e32 v62, 0x8c, v54
	v_med3_i32 v62, v62, 0, v213
	v_add_u32_e32 v65, s27, v62
	v_add_u32_e32 v62, 0xc0, v54
	v_med3_i32 v62, v62, 0, v213
	v_add_u32_e32 v70, s27, v62
	v_add_u32_e32 v62, 0xc4, v54
	v_add_u32_e32 v55, 0x80, v54
	v_add_u32_e32 v56, 0x84, v54
	v_add_u32_e32 v57, 0x88, v54
	v_med3_i32 v62, v62, 0, v213
	v_med3_i32 v55, v55, 0, v213
	v_med3_i32 v56, v56, 0, v213
	v_med3_i32 v57, v57, 0, v213
	v_add_u32_e32 v71, s27, v62
	v_add_u32_e32 v62, 0xc8, v54
	v_add_u32_e32 v54, 0xcc, v54
	v_add_u32_e32 v55, s27, v55
	v_add_u32_e32 v56, s27, v56
	v_add_u32_e32 v57, s27, v57
	v_med3_i32 v62, v62, 0, v213
	v_med3_i32 v54, v54, 0, v213
	v_add_u32_e32 v72, s27, v62
	v_add_u32_e32 v73, s27, v54
	ds_read_b32 v62, v55
	ds_read_b32 v63, v56
	ds_read_b32 v64, v57
	ds_read_b32 v65, v65
	ds_read_b32 v54, v70
	ds_read_b32 v55, v71
	ds_read_b32 v56, v72
	ds_read_b32 v57, v73
	s_mov_b64 s[22:23], 0
